# grid barrier: L1 invalidate issued by wave 1 at arrival (the leader never waits for it)
# baseline (speedup 1.0000x reference)
; DI void grid_bar(unsigned* bar, volatile LAS unsigned* st, int wid) {
;     ...
;                 __builtin_amdgcn_fence(__ATOMIC_ACQUIRE, "agent");
;                 asm volatile("s_waitcnt vmcnt(0)" ::: "memory");
;             }
;         }
;     }
;     __syncthreads();
.LBB0_294:
	s_or_b64 exec, exec, s[12:13]
	s_waitcnt vmcnt(0)
.LBB0_295:
	s_or_b64 exec, exec, s[4:5]
	s_branch .LBB0_296
.Lbi_0:
	s_cmp_gt_u32 s88, 127
	s_cbranch_scc1 .LBB0_296
	buffer_inv sc1
	s_waitcnt vmcnt(0)

; DI void grid_bar(unsigned* bar, volatile LAS unsigned* st, int wid) {
;     ...
;         }
;     }
;     __syncthreads();
.LBB0_451:
	s_or_b64 exec, exec, s[12:13]
	s_waitcnt vmcnt(0)
.LBB0_452:
	s_or_b64 exec, exec, s[4:5]
	s_branch .LBB0_453

; DI void grid_bar(unsigned* bar, volatile LAS unsigned* st, int wid) {
;     ...
;         }
;     }
;     __syncthreads();
.LBB0_524:
	s_or_b64 exec, exec, s[12:13]
	s_waitcnt vmcnt(0)
.LBB0_525:
	s_or_b64 exec, exec, s[4:5]
	s_branch .LBB0_526

; DI void grid_bar(unsigned* bar, volatile LAS unsigned* st, int wid) {
;     ...
;         }
;     }
;     __syncthreads();
.LBB0_599:
	s_or_b64 exec, exec, s[12:13]
	s_waitcnt vmcnt(0)
.LBB0_600:
	s_or_b64 exec, exec, s[4:5]
	s_branch .LBB0_601

; DI void grid_bar(unsigned* bar, volatile LAS unsigned* st, int wid) {
;     ...
;         }
;     }
;     __syncthreads();
.LBB0_694:
	s_or_b64 exec, exec, s[12:13]
	s_waitcnt vmcnt(0)
.LBB0_695:
	s_or_b64 exec, exec, s[4:5]
	s_branch .LBB0_696

; DI void grid_bar(unsigned* bar, volatile LAS unsigned* st, int wid) {
;     ...
;         }
;     }
;     __syncthreads();
.LBB0_763:
	s_or_b64 exec, exec, s[12:13]
	s_waitcnt vmcnt(0)
.LBB0_764:
	s_or_b64 exec, exec, s[4:5]
	s_branch .LBB0_765

; DI void grid_bar(unsigned* bar, volatile LAS unsigned* st, int wid) {
;     ...
;         }
;     }
;     __syncthreads();
.LBB0_858:
	s_or_b64 exec, exec, s[12:13]
	s_waitcnt vmcnt(0)
.LBB0_859:
	s_or_b64 exec, exec, s[4:5]
	s_branch .LBB0_860

; DI void grid_bar(unsigned* bar, volatile LAS unsigned* st, int wid) {
;     ...
;         }
;     }
;     __syncthreads();
.LBB0_951:
	s_or_b64 exec, exec, s[12:13]
	s_waitcnt vmcnt(0)
.LBB0_952:
	s_or_b64 exec, exec, s[4:5]
	s_branch .LBB0_953

; DI void grid_bar(unsigned* bar, volatile LAS unsigned* st, int wid) {
;     ...
;         }
;     }
;     __syncthreads();
.LBB0_1071:
	s_or_b64 exec, exec, s[2:3]
	s_branch .LBB0_1072

; DI void grid_bar(unsigned* bar, volatile LAS unsigned* st, int wid) {
;     ...
;         }
;     }
;     __syncthreads();
.LBB0_1249:
	s_or_b64 exec, exec, s[12:13]
	s_waitcnt vmcnt(0)
.LBB0_1250:
	s_or_b64 exec, exec, s[4:5]
	s_branch .LBB0_1251

; DI void grid_bar(unsigned* bar, volatile LAS unsigned* st, int wid) {
;     ...
;         }
;     }
;     __syncthreads();
.LBB0_1318:
	s_or_b64 exec, exec, s[12:13]
	s_waitcnt vmcnt(0)
.LBB0_1319:
	s_or_b64 exec, exec, s[4:5]
	s_branch .LBB0_1320

; DI void grid_bar(unsigned* bar, volatile LAS unsigned* st, int wid) {
;     ...
;         }
;     }
;     __syncthreads();
.LBB0_1413:
	s_or_b64 exec, exec, s[12:13]
	s_waitcnt vmcnt(0)
.LBB0_1414:
	s_or_b64 exec, exec, s[4:5]
	s_branch .LBB0_1415
